# v16_peel
# speedup vs baseline: 1.0150x; 1.0020x over previous
; #define STAGE(PP, RSRC, br, kt) do { const int _so = ((br) * K + (kt) * BK) * 2; \
;       __builtin_amdgcn_raw_ptr_buffer_load_lds(RSRC, LDSP((char*)(PP) + ldsoff), 16, voff0, _so, 0, 0); \
;       __builtin_amdgcn_raw_ptr_buffer_load_lds(RSRC, LDSP((char*)(PP) + ldsoff + 8192), 16, voff1, _so, 0, 0); \
;     } while (0)
; #define LDA(dst, b, h) for (int m = 0; m < 4; ++m) for (int k = 0; k < 2; ++k) \
;     dst[m][k] = *reinterpret_cast<const bf16x8*>((char*)SA(b, h) + lds_byte(wr * 64 + m * 16 + fr, k * 32 + fq * 8))
; #define LDB(dst, b, h) for (int n = 0; n < 2; ++n) for (int k = 0; k < 2; ++k) \
;     dst[n][k] = *reinterpret_cast<const bf16x8*>((char*)SB(b, h) + lds_byte(wc * 32 + n * 16 + fr, k * 32 + fq * 8))
; #define MMA(ai, bj, At_, Bt_) do { __builtin_amdgcn_s_setprio(1); \
;     for (int m = 0; m < 4; ++m) for (int n = 0; n < 2; ++n) for (int k = 0; k < 2; ++k) \
;       acc[ai][bj][m][n] = __builtin_amdgcn_mfma_f32_16x16x32_bf16(At_[m][k], Bt_[n][k], acc[ai][bj][m][n], 0, 0, 0); \
;     __builtin_amdgcn_s_setprio(0); } while (0)
; #define WAIT_V(n) asm volatile("s_waitcnt vmcnt(" #n ")" ::: "memory")
; #define WAIT_L(n) asm volatile("s_waitcnt lgkmcnt(" #n ")" ::: "memory")
; #define BAR __builtin_amdgcn_s_barrier()
; __device__ __forceinline__ void gemm_tile(const Params& P, const GArgs& ga, const TileDesc& td, int wid_s) {
;     ...
;   f32x4 acc[2][2][4][2] = {};
;   bf16x8 At[4][2], B0[2][2], B1[2][2];
;   const int nt = nkt;
;   STAGE(SB(0, 0), Bt, bcol, 0); STAGE(SA(0, 0), A, brow, 0);
;   STAGE(SB(0, 1), Bt, bcol + HALF, 0); STAGE(SA(0, 1), A, brow + HALF, 0);
;   if (wr == 1) BAR;
;   WAIT_V(4); BAR;
;   STAGE(SB(1, 0), Bt, bcol, 1); STAGE(SA(1, 0), A, brow, 1); STAGE(SB(1, 1), Bt, bcol + HALF, 1);
;   WAIT_V(6); BAR;
;   LDB(B0, 0, 0);
;   for (int t = 0; t < nt - 2; t += 2) {
;     LDA(At, 0, 0); STAGE(SA(1, 1), A, brow + HALF, t + 1);
;     WAIT_L(8); BAR; WAIT_L(0); MMA(0, 0, At, B0); BAR; SCHED;
;     LDB(B1, 0, 1); STAGE(SB(0, 0), Bt, bcol, t + 2);
;     BAR; WAIT_L(0); MMA(0, 1, At, B1); BAR;
;     LDA(At, 0, 1); STAGE(SA(0, 0), A, brow, t + 2);
;     WAIT_V(4); BAR; WAIT_L(0); MMA(1, 0, At, B0); BAR; SCHED;
;     LDB(B0, 1, 0); STAGE(SB(0, 1), Bt, bcol + HALF, t + 2);
;     BAR; MMA(1, 1, At, B1); BAR;
;     LDA(At, 1, 0); STAGE(SA(0, 1), A, brow + HALF, t + 2);
;     WAIT_L(8); BAR; WAIT_L(0); MMA(0, 0, At, B0); BAR; SCHED;
.LBB0_306:
	s_andn2_b64 vcc, exec, s[0:1]
	v_mov_b32_e32 v141, 0
	s_cbranch_vccnz .LBB0_310
	v_and_b32_e32 v22, 0x3c0, v22
	v_and_b32_e32 v23, 32, v23
	v_bitop3_b32 v150, v22, v23, v18 bitop3:0x36
	v_lshlrev_b32_e32 v23, 6, v21
	v_lshlrev_b32_e32 v21, 2, v21
	v_and_b32_e32 v23, 0x3c0, v23
	v_and_b32_e32 v21, 32, v21
	v_bitop3_b32 v152, v23, v21, v18 bitop3:0x36
	v_lshlrev_b32_e32 v23, 6, v20
	v_lshlrev_b32_e32 v20, 2, v20
	v_and_b32_e32 v23, 0x3c0, v23
	v_and_b32_e32 v20, 32, v20
	s_add_i32 s1, 0, 0x14000
	v_bitop3_b32 v154, v23, v20, v18 bitop3:0x36
	v_lshlrev_b32_e32 v23, 6, v19
	v_lshlrev_b32_e32 v19, 2, v19
	v_add_u32_e32 v24, s1, v146
	s_add_i32 s1, 0, 0x18000
	v_and_b32_e32 v23, 0x3c0, v23
	v_and_b32_e32 v19, 32, v19
	v_add_u32_e32 v25, s1, v146
	s_add_i32 s1, 0, 0x1c000
	v_bitop3_b32 v156, v23, v19, v18 bitop3:0x36
	v_add_u32_e32 v26, s1, v146
	v_add_u32_e32 v22, 0, v150
	v_add_u32_e32 v21, 0, v152
	v_add_u32_e32 v20, 0, v154
	v_add_u32_e32 v19, 0, v156
	s_add_i32 s1, s84, 0x80
	s_add_i32 s6, s92, 0x80
	v_mov_b32_e32 v18, 0
	s_add_i32 s0, s17, -2
	v_or_b32_e32 v151, 0x400, v159
	v_or_b32_e32 v153, 0x400, v161
	v_or_b32_e32 v155, 0x400, v160
	v_or_b32_e32 v157, 0x400, v158
	s_mul_i32 s1, s48, s1
	s_mul_i32 s98, s48, s6
	s_mov_b32 s99, 0
	v_add_u32_e32 v163, v22, v159
	v_add_u32_e32 v164, v21, v161
	v_add_u32_e32 v165, v20, v160
	v_add_u32_e32 v166, v19, v158
	v_add_u32_e32 v167, v24, v147
	v_add_u32_e32 v168, v25, v147
	v_add_u32_e32 v169, v26, v147
	s_mov_b32 vcc_lo, 0
	s_waitcnt vmcnt(15)
	s_waitcnt vmcnt(14)
	s_add_i32 s38, s1, s99
	s_add_i32 s6, s38, 0x80
	s_mov_b32 m0, s23
	ds_read_b128 v[170:173], v163
	ds_read_b128 v[174:177], v163 offset:1024
	ds_read_b128 v[178:181], v164
	ds_read_b128 v[182:185], v164 offset:1024
	ds_read_b128 v[186:189], v165
	ds_read_b128 v[190:193], v165 offset:1024
	ds_read_b128 v[194:197], v166
	ds_read_b128 v[204:207], v166 offset:1024
	buffer_load_dwordx4 v148, s[8:11], s6 offen lds
	s_mov_b32 m0, s22
	s_nop 0
	buffer_load_dwordx4 v149, s[8:11], s6 offen lds
	s_mul_i32 s6, s49, s15
	s_add_i32 s58, s6, s99
	s_mov_b32 m0, s88
	s_add_i32 vcc_hi, s58, 0x100
	s_mov_b32 s6, s10
	s_mov_b32 s7, s11
	ds_read_b128 v[208:211], v167
	ds_read_b128 v[212:215], v167 offset:1024
	ds_read_b128 v[216:219], v167 offset:2048
	ds_read_b128 v[220:223], v167 offset:3072
	buffer_load_dwordx4 v148, s[4:7], vcc_hi offen lds
	s_mov_b32 m0, s89
	s_add_i32 vcc_lo, vcc_lo, 2
	buffer_load_dwordx4 v149, s[4:7], vcc_hi offen lds
	s_waitcnt vmcnt(8) lgkmcnt(0)
	s_barrier
	s_setprio 1
	v_mfma_f32_16x16x32_bf16 v[138:141], v[170:173], v[2:5], 0
	v_mfma_f32_16x16x32_bf16 v[142:145], v[170:173], v[10:13], 0
	v_mfma_f32_16x16x32_bf16 v[134:137], v[178:181], v[2:5], 0
	v_mfma_f32_16x16x32_bf16 v[130:133], v[178:181], v[10:13], 0
	v_mfma_f32_16x16x32_bf16 v[126:129], v[186:189], v[2:5], 0
	v_mfma_f32_16x16x32_bf16 v[122:125], v[186:189], v[10:13], 0
	v_mfma_f32_16x16x32_bf16 v[118:121], v[194:197], v[2:5], 0
	v_mfma_f32_16x16x32_bf16 v[114:117], v[194:197], v[10:13], 0
	v_mfma_f32_16x16x32_bf16 v[138:141], v[174:177], v[6:9], v[138:141]
	v_mfma_f32_16x16x32_bf16 v[142:145], v[174:177], v[14:17], v[142:145]
	v_mfma_f32_16x16x32_bf16 v[134:137], v[182:185], v[6:9], v[134:137]
	v_mfma_f32_16x16x32_bf16 v[130:133], v[182:185], v[14:17], v[130:133]
	v_mfma_f32_16x16x32_bf16 v[126:129], v[190:193], v[6:9], v[126:129]
	v_mfma_f32_16x16x32_bf16 v[122:125], v[190:193], v[14:17], v[122:125]
	v_mfma_f32_16x16x32_bf16 v[118:121], v[204:207], v[6:9], v[118:121]
	v_mfma_f32_16x16x32_bf16 v[114:117], v[204:207], v[14:17], v[114:117]
	v_mfma_f32_16x16x32_bf16 v[110:113], v[170:173], v[208:211], 0
	v_mfma_f32_16x16x32_bf16 v[106:109], v[170:173], v[216:219], 0
	v_mfma_f32_16x16x32_bf16 v[102:105], v[178:181], v[208:211], 0
	v_mfma_f32_16x16x32_bf16 v[98:101], v[178:181], v[216:219], 0
	v_mfma_f32_16x16x32_bf16 v[94:97], v[186:189], v[208:211], 0
	v_mfma_f32_16x16x32_bf16 v[90:93], v[186:189], v[216:219], 0
	v_mfma_f32_16x16x32_bf16 v[86:89], v[194:197], v[208:211], 0
	v_mfma_f32_16x16x32_bf16 v[82:85], v[194:197], v[216:219], 0
	v_mfma_f32_16x16x32_bf16 v[110:113], v[174:177], v[212:215], v[110:113]
	v_mfma_f32_16x16x32_bf16 v[106:109], v[174:177], v[220:223], v[106:109]
	v_mfma_f32_16x16x32_bf16 v[102:105], v[182:185], v[212:215], v[102:105]
	v_mfma_f32_16x16x32_bf16 v[98:101], v[182:185], v[220:223], v[98:101]
	v_mfma_f32_16x16x32_bf16 v[94:97], v[190:193], v[212:215], v[94:97]
	v_mfma_f32_16x16x32_bf16 v[90:93], v[190:193], v[220:223], v[90:93]
	v_mfma_f32_16x16x32_bf16 v[86:89], v[204:207], v[212:215], v[86:89]
	v_mfma_f32_16x16x32_bf16 v[82:85], v[204:207], v[220:223], v[82:85]
	s_setprio 0
	s_mul_i32 vcc_hi, s49, s86
	s_add_i32 s40, vcc_hi, s99
	s_add_i32 vcc_hi, s40, 0x100
	s_mov_b32 m0, s52
	s_barrier
	ds_read_b128 v[170:173], v163 offset:16384
	ds_read_b128 v[174:177], v163 offset:17408
	ds_read_b128 v[178:181], v164 offset:16384
	ds_read_b128 v[182:185], v164 offset:17408
	ds_read_b128 v[186:189], v165 offset:16384
	ds_read_b128 v[190:193], v165 offset:17408
	ds_read_b128 v[194:197], v166 offset:16384
	ds_read_b128 v[204:207], v166 offset:17408
	buffer_load_dwordx4 v148, s[8:11], vcc_hi offen lds
	s_mov_b32 m0, s94
	s_nop 0
	buffer_load_dwordx4 v149, s[8:11], vcc_hi offen lds
	s_add_i32 s33, s98, s99
	s_add_i32 vcc_hi, s33, 0x100
	s_mov_b32 m0, s95
	ds_read_b128 v[232:235], v168
	ds_read_b128 v[236:239], v168 offset:1024
	ds_read_b128 v[240:243], v168 offset:2048
	ds_read_b128 v[244:247], v168 offset:3072
	buffer_load_dwordx4 v148, s[4:7], vcc_hi offen lds
	s_mov_b32 m0, s3
	s_nop 0
	buffer_load_dwordx4 v149, s[4:7], vcc_hi offen lds
	s_waitcnt vmcnt(8) lgkmcnt(0)
	s_barrier
; #define STAGE(PP, RSRC, br, kt) do { const int _so = ((br) * K + (kt) * BK) * 2; \
;       __builtin_amdgcn_raw_ptr_buffer_load_lds(RSRC, LDSP((char*)(PP) + ldsoff), 16, voff0, _so, 0, 0); \
;       __builtin_amdgcn_raw_ptr_buffer_load_lds(RSRC, LDSP((char*)(PP) + ldsoff + 8192), 16, voff1, _so, 0, 0); \
;     } while (0)
; #define LDA(dst, b, h) for (int m = 0; m < 4; ++m) for (int k = 0; k < 2; ++k) \
;     dst[m][k] = *reinterpret_cast<const bf16x8*>((char*)SA(b, h) + lds_byte(wr * 64 + m * 16 + fr, k * 32 + fq * 8))
; #define LDB(dst, b, h) for (int n = 0; n < 2; ++n) for (int k = 0; k < 2; ++k) \
;     dst[n][k] = *reinterpret_cast<const bf16x8*>((char*)SB(b, h) + lds_byte(wc * 32 + n * 16 + fr, k * 32 + fq * 8))
; #define MMA(ai, bj, At_, Bt_) do { __builtin_amdgcn_s_setprio(1); \
;     for (int m = 0; m < 4; ++m) for (int n = 0; n < 2; ++n) for (int k = 0; k < 2; ++k) \
;       acc[ai][bj][m][n] = __builtin_amdgcn_mfma_f32_16x16x32_bf16(At_[m][k], Bt_[n][k], acc[ai][bj][m][n], 0, 0, 0); \
;     __builtin_amdgcn_s_setprio(0); } while (0)
; #define WAIT_V(n) asm volatile("s_waitcnt vmcnt(" #n ")" ::: "memory")
; #define WAIT_L(n) asm volatile("s_waitcnt lgkmcnt(" #n ")" ::: "memory")
; #define BAR __builtin_amdgcn_s_barrier()
; #define SCHED __builtin_amdgcn_sched_barrier(0)
; __device__ __forceinline__ void gemm_tile(const Params& P, const GArgs& ga, const TileDesc& td, int wid_s) {
;     ...
;   for (int t = 0; t < nt - 2; t += 2) {
;     LDA(At, 0, 0); STAGE(SA(1, 1), A, brow + HALF, t + 1);
;     WAIT_L(8); BAR; WAIT_L(0); MMA(0, 0, At, B0); BAR; SCHED;
;     LDB(B1, 0, 1); STAGE(SB(0, 0), Bt, bcol, t + 2);
;     BAR; WAIT_L(0); MMA(0, 1, At, B1); BAR;
;     LDA(At, 0, 1); STAGE(SA(0, 0), A, brow, t + 2);
;     WAIT_V(4); BAR; WAIT_L(0); MMA(1, 0, At, B0); BAR; SCHED;
;     LDB(B0, 1, 0); STAGE(SB(0, 1), Bt, bcol + HALF, t + 2);
;     BAR; MMA(1, 1, At, B1); BAR;
;     LDA(At, 1, 0); STAGE(SA(0, 1), A, brow + HALF, t + 2);
;     WAIT_L(8); BAR; WAIT_L(0); MMA(0, 0, At, B0); BAR; SCHED;
	s_setprio 1
	v_mfma_f32_16x16x32_bf16 v[78:81], v[170:173], v[2:5], 0
	v_mfma_f32_16x16x32_bf16 v[70:73], v[178:181], v[2:5], 0
	v_mfma_f32_16x16x32_bf16 v[62:65], v[186:189], v[2:5], 0
	v_mfma_f32_16x16x32_bf16 v[248:251], v[194:197], v[2:5], 0
	v_mfma_f32_16x16x32_bf16 v[78:81], v[174:177], v[6:9], v[78:81]
	v_mfma_f32_16x16x32_bf16 v[74:77], v[170:173], v[10:13], 0
	v_mfma_f32_16x16x32_bf16 v[70:73], v[182:185], v[6:9], v[70:73]
	v_mfma_f32_16x16x32_bf16 v[66:69], v[178:181], v[10:13], 0
	v_mfma_f32_16x16x32_bf16 v[62:65], v[190:193], v[6:9], v[62:65]
	v_mfma_f32_16x16x32_bf16 v[58:61], v[186:189], v[10:13], 0
	v_mfma_f32_16x16x32_bf16 v[248:251], v[204:207], v[6:9], v[248:251]
	v_mfma_f32_16x16x32_bf16 v[252:255], v[194:197], v[10:13], 0
	v_mfma_f32_16x16x32_bf16 v[74:77], v[174:177], v[14:17], v[74:77]
	v_mfma_f32_16x16x32_bf16 v[66:69], v[182:185], v[14:17], v[66:69]
	v_mfma_f32_16x16x32_bf16 v[58:61], v[190:193], v[14:17], v[58:61]
	v_mfma_f32_16x16x32_bf16 v[252:255], v[204:207], v[14:17], v[252:255]
	v_mfma_f32_16x16x32_bf16 v[46:49], v[170:173], v[208:211], 0
	v_mfma_f32_16x16x32_bf16 v[42:45], v[170:173], v[216:219], 0
	v_mfma_f32_16x16x32_bf16 v[38:41], v[178:181], v[208:211], 0
	v_mfma_f32_16x16x32_bf16 v[34:37], v[178:181], v[216:219], 0
	v_mfma_f32_16x16x32_bf16 v[30:33], v[186:189], v[208:211], 0
	v_mfma_f32_16x16x32_bf16 v[26:29], v[186:189], v[216:219], 0
	v_mfma_f32_16x16x32_bf16 v[22:25], v[194:197], v[208:211], 0
	v_mfma_f32_16x16x32_bf16 v[18:21], v[194:197], v[216:219], 0
	v_mfma_f32_16x16x32_bf16 v[46:49], v[174:177], v[212:215], v[46:49]
	v_mfma_f32_16x16x32_bf16 v[42:45], v[174:177], v[220:223], v[42:45]
	v_mfma_f32_16x16x32_bf16 v[38:41], v[182:185], v[212:215], v[38:41]
	v_mfma_f32_16x16x32_bf16 v[34:37], v[182:185], v[220:223], v[34:37]
	v_mfma_f32_16x16x32_bf16 v[30:33], v[190:193], v[212:215], v[30:33]
	v_mfma_f32_16x16x32_bf16 v[26:29], v[190:193], v[220:223], v[26:29]
	v_mfma_f32_16x16x32_bf16 v[22:25], v[204:207], v[212:215], v[22:25]
	v_mfma_f32_16x16x32_bf16 v[18:21], v[204:207], v[220:223], v[18:21]
	s_setprio 0
	s_addk_i32 s38, 0x100
	s_mov_b32 m0, s57
	s_barrier
	ds_read_b128 v[54:57], v163 offset:32768
	ds_read_b128 v[170:173], v163 offset:33792
	ds_read_b128 v[174:177], v164 offset:32768
	ds_read_b128 v[178:181], v164 offset:33792
	ds_read_b128 v[182:185], v165 offset:32768
	ds_read_b128 v[186:189], v165 offset:33792
	ds_read_b128 v[190:193], v166 offset:32768
	ds_read_b128 v[194:197], v166 offset:33792
	buffer_load_dwordx4 v148, s[8:11], s38 offen lds
	s_mov_b32 m0, s56
	s_nop 0
	buffer_load_dwordx4 v149, s[8:11], s38 offen lds
	s_addk_i32 s58, 0x180
	s_mov_b32 m0, s75
	ds_read_b128 v[204:207], v169
	ds_read_b128 v[208:211], v169 offset:1024
	ds_read_b128 v[212:215], v169 offset:2048
	ds_read_b128 v[216:219], v169 offset:3072
	buffer_load_dwordx4 v148, s[4:7], s58 offen lds
	s_mov_b32 m0, s74
	s_nop 0
	buffer_load_dwordx4 v149, s[4:7], s58 offen lds
	s_waitcnt vmcnt(8) lgkmcnt(0)
	s_barrier
	s_setprio 1
	v_mfma_f32_16x16x32_bf16 v[138:141], v[54:57], v[232:235], v[138:141]
	v_mfma_f32_16x16x32_bf16 v[142:145], v[54:57], v[240:243], v[142:145]
	v_mfma_f32_16x16x32_bf16 v[134:137], v[174:177], v[232:235], v[134:137]
	v_mfma_f32_16x16x32_bf16 v[130:133], v[174:177], v[240:243], v[130:133]
	v_mfma_f32_16x16x32_bf16 v[126:129], v[182:185], v[232:235], v[126:129]
	v_mfma_f32_16x16x32_bf16 v[122:125], v[182:185], v[240:243], v[122:125]
	v_mfma_f32_16x16x32_bf16 v[118:121], v[190:193], v[232:235], v[118:121]
	v_mfma_f32_16x16x32_bf16 v[114:117], v[190:193], v[240:243], v[114:117]
	v_mfma_f32_16x16x32_bf16 v[138:141], v[170:173], v[236:239], v[138:141]
	v_mfma_f32_16x16x32_bf16 v[142:145], v[170:173], v[244:247], v[142:145]
	v_mfma_f32_16x16x32_bf16 v[134:137], v[178:181], v[236:239], v[134:137]
	v_mfma_f32_16x16x32_bf16 v[130:133], v[178:181], v[244:247], v[130:133]
	v_mfma_f32_16x16x32_bf16 v[126:129], v[186:189], v[236:239], v[126:129]
	v_mfma_f32_16x16x32_bf16 v[122:125], v[186:189], v[244:247], v[122:125]
	v_mfma_f32_16x16x32_bf16 v[118:121], v[194:197], v[236:239], v[118:121]
	v_mfma_f32_16x16x32_bf16 v[114:117], v[194:197], v[244:247], v[114:117]
	v_mfma_f32_16x16x32_bf16 v[110:113], v[54:57], v[204:207], v[110:113]
	v_mfma_f32_16x16x32_bf16 v[54:57], v[54:57], v[212:215], v[106:109]
	v_mfma_f32_16x16x32_bf16 v[106:109], v[170:173], v[216:219], v[54:57]
	v_mfma_f32_16x16x32_bf16 v[54:57], v[174:177], v[204:207], v[102:105]
	v_mfma_f32_16x16x32_bf16 v[102:105], v[178:181], v[208:211], v[54:57]
	v_mfma_f32_16x16x32_bf16 v[54:57], v[174:177], v[212:215], v[98:101]
	v_mfma_f32_16x16x32_bf16 v[98:101], v[178:181], v[216:219], v[54:57]
	v_mfma_f32_16x16x32_bf16 v[54:57], v[182:185], v[204:207], v[94:97]
	v_mfma_f32_16x16x32_bf16 v[94:97], v[186:189], v[208:211], v[54:57]
	v_mfma_f32_16x16x32_bf16 v[54:57], v[182:185], v[212:215], v[90:93]
	v_mfma_f32_16x16x32_bf16 v[90:93], v[186:189], v[216:219], v[54:57]
	v_mfma_f32_16x16x32_bf16 v[54:57], v[190:193], v[204:207], v[86:89]
	v_mfma_f32_16x16x32_bf16 v[86:89], v[194:197], v[208:211], v[54:57]
	v_mfma_f32_16x16x32_bf16 v[54:57], v[190:193], v[212:215], v[82:85]
	v_mfma_f32_16x16x32_bf16 v[110:113], v[170:173], v[208:211], v[110:113]
	v_mfma_f32_16x16x32_bf16 v[82:85], v[194:197], v[216:219], v[54:57]
	s_setprio 0
	s_addk_i32 s40, 0x180
	s_mov_b32 m0, s83
	s_barrier
; #define STAGE(PP, RSRC, br, kt) do { const int _so = ((br) * K + (kt) * BK) * 2; \
;       __builtin_amdgcn_raw_ptr_buffer_load_lds(RSRC, LDSP((char*)(PP) + ldsoff), 16, voff0, _so, 0, 0); \
;       __builtin_amdgcn_raw_ptr_buffer_load_lds(RSRC, LDSP((char*)(PP) + ldsoff + 8192), 16, voff1, _so, 0, 0); \
;     } while (0)
; #define LDA(dst, b, h) for (int m = 0; m < 4; ++m) for (int k = 0; k < 2; ++k) \
;     dst[m][k] = *reinterpret_cast<const bf16x8*>((char*)SA(b, h) + lds_byte(wr * 64 + m * 16 + fr, k * 32 + fq * 8))
; #define LDB(dst, b, h) for (int n = 0; n < 2; ++n) for (int k = 0; k < 2; ++k) \
;     dst[n][k] = *reinterpret_cast<const bf16x8*>((char*)SB(b, h) + lds_byte(wc * 32 + n * 16 + fr, k * 32 + fq * 8))
; #define MMA(ai, bj, At_, Bt_) do { __builtin_amdgcn_s_setprio(1); \
;     for (int m = 0; m < 4; ++m) for (int n = 0; n < 2; ++n) for (int k = 0; k < 2; ++k) \
;       acc[ai][bj][m][n] = __builtin_amdgcn_mfma_f32_16x16x32_bf16(At_[m][k], Bt_[n][k], acc[ai][bj][m][n], 0, 0, 0); \
;     __builtin_amdgcn_s_setprio(0); } while (0)
; #define WAIT_V(n) asm volatile("s_waitcnt vmcnt(" #n ")" ::: "memory")
; #define WAIT_L(n) asm volatile("s_waitcnt lgkmcnt(" #n ")" ::: "memory")
; #define BAR __builtin_amdgcn_s_barrier()
; #define SCHED __builtin_amdgcn_sched_barrier(0)
; __device__ __forceinline__ void gemm_tile(const Params& P, const GArgs& ga, const TileDesc& td, int wid_s) {
;     ...
;     LDB(B1, 1, 1); STAGE(SB(1, 0), Bt, bcol, t + 3);
;     BAR; WAIT_L(0); MMA(0, 1, At, B1); BAR;
;     LDA(At, 1, 1); STAGE(SA(1, 0), A, brow, t + 3);
;     WAIT_V(4); BAR; WAIT_L(0); MMA(1, 0, At, B0); BAR; SCHED;
;     LDB(B0, 0, 0); STAGE(SB(1, 1), Bt, bcol + HALF, t + 3);
;     BAR; MMA(1, 1, At, B1); BAR;
;   }
	ds_read_b128 v[170:173], v163 offset:49152
	ds_read_b128 v[174:177], v163 offset:50176
	ds_read_b128 v[178:181], v164 offset:49152
	ds_read_b128 v[182:185], v164 offset:50176
	ds_read_b128 v[186:189], v165 offset:49152
	ds_read_b128 v[190:193], v165 offset:50176
	ds_read_b128 v[194:197], v166 offset:49152
	ds_read_b128 v[220:223], v166 offset:50176
	buffer_load_dwordx4 v148, s[8:11], s40 offen lds
	s_mov_b32 m0, s82
	s_nop 0
	buffer_load_dwordx4 v149, s[8:11], s40 offen lds
	s_mov_b32 m0, s69
	s_addk_i32 s33, 0x180
	buffer_load_dwordx4 v148, s[4:7], s33 offen lds
	s_mov_b32 m0, s68
	s_nop 0
	buffer_load_dwordx4 v149, s[4:7], s33 offen lds
	ds_read_b128 v[2:5], v162
	ds_read_b128 v[6:9], v162 offset:1024
	ds_read_b128 v[10:13], v162 offset:2048
	ds_read_b128 v[14:17], v162 offset:3072
	s_waitcnt vmcnt(8) lgkmcnt(0)
	s_barrier
	s_setprio 1
	v_mfma_f32_16x16x32_bf16 v[54:57], v[170:173], v[232:235], v[78:81]
	v_mfma_f32_16x16x32_bf16 v[78:81], v[174:177], v[236:239], v[54:57]
	v_mfma_f32_16x16x32_bf16 v[54:57], v[170:173], v[240:243], v[74:77]
	v_mfma_f32_16x16x32_bf16 v[74:77], v[174:177], v[244:247], v[54:57]
	v_mfma_f32_16x16x32_bf16 v[54:57], v[178:181], v[232:235], v[70:73]
	v_mfma_f32_16x16x32_bf16 v[70:73], v[182:185], v[236:239], v[54:57]
	v_mfma_f32_16x16x32_bf16 v[54:57], v[178:181], v[240:243], v[66:69]
	v_mfma_f32_16x16x32_bf16 v[66:69], v[182:185], v[244:247], v[54:57]
	v_mfma_f32_16x16x32_bf16 v[54:57], v[186:189], v[232:235], v[62:65]
	v_mfma_f32_16x16x32_bf16 v[62:65], v[190:193], v[236:239], v[54:57]
	v_mfma_f32_16x16x32_bf16 v[54:57], v[186:189], v[240:243], v[58:61]
	v_mfma_f32_16x16x32_bf16 v[248:251], v[194:197], v[232:235], v[248:251]
	v_mfma_f32_16x16x32_bf16 v[58:61], v[190:193], v[244:247], v[54:57]
	v_mfma_f32_16x16x32_bf16 v[54:57], v[220:223], v[236:239], v[248:251]
	v_mfma_f32_16x16x32_bf16 v[248:251], v[194:197], v[240:243], v[252:255]
	v_mfma_f32_16x16x32_bf16 v[50:53], v[220:223], v[244:247], v[248:251]
	v_mfma_f32_16x16x32_bf16 v[46:49], v[170:173], v[204:207], v[46:49]
	v_mfma_f32_16x16x32_bf16 v[42:45], v[170:173], v[212:215], v[42:45]
	v_mfma_f32_16x16x32_bf16 v[38:41], v[178:181], v[204:207], v[38:41]
	v_mfma_f32_16x16x32_bf16 v[34:37], v[178:181], v[212:215], v[34:37]
	v_mfma_f32_16x16x32_bf16 v[30:33], v[186:189], v[204:207], v[30:33]
	v_mfma_f32_16x16x32_bf16 v[26:29], v[186:189], v[212:215], v[26:29]
	v_mfma_f32_16x16x32_bf16 v[22:25], v[194:197], v[204:207], v[22:25]
	v_mfma_f32_16x16x32_bf16 v[18:21], v[194:197], v[212:215], v[18:21]
	v_mfma_f32_16x16x32_bf16 v[46:49], v[174:177], v[208:211], v[46:49]
	v_mfma_f32_16x16x32_bf16 v[42:45], v[174:177], v[216:219], v[42:45]
	v_mfma_f32_16x16x32_bf16 v[38:41], v[182:185], v[208:211], v[38:41]
	v_mfma_f32_16x16x32_bf16 v[34:37], v[182:185], v[216:219], v[34:37]
	v_mfma_f32_16x16x32_bf16 v[30:33], v[190:193], v[208:211], v[30:33]
	v_mfma_f32_16x16x32_bf16 v[26:29], v[190:193], v[216:219], v[26:29]
	v_mfma_f32_16x16x32_bf16 v[22:25], v[220:223], v[208:211], v[22:25]
	v_mfma_f32_16x16x32_bf16 v[18:21], v[220:223], v[216:219], v[18:21]
	s_setprio 0
	s_addk_i32 s99, 0x100
	s_cmp_lt_i32 vcc_lo, s0
	s_barrier
	s_cbranch_scc0 .Lml_exit

; #define STAGE(PP, RSRC, br, kt) do { const int _so = ((br) * K + (kt) * BK) * 2; \
;       __builtin_amdgcn_raw_ptr_buffer_load_lds(RSRC, LDSP((char*)(PP) + ldsoff), 16, voff0, _so, 0, 0); \
;       __builtin_amdgcn_raw_ptr_buffer_load_lds(RSRC, LDSP((char*)(PP) + ldsoff + 8192), 16, voff1, _so, 0, 0); \
;     } while (0)
; #define LDA(dst, b, h) for (int m = 0; m < 4; ++m) for (int k = 0; k < 2; ++k) \
;     dst[m][k] = *reinterpret_cast<const bf16x8*>((char*)SA(b, h) + lds_byte(wr * 64 + m * 16 + fr, k * 32 + fq * 8))
; __device__ __forceinline__ void gemm_tile(const Params& P, const GArgs& ga, const TileDesc& td, int wid_s) {
;     ...
;   }
;   { LDA(At, 0, 0); STAGE(SA(1, 1), A, brow + HALF, nt - 1);
.Lml_exit:
	s_mov_b64 s[98:99], s[50:51]
	s_mov_b32 s58, s90
	s_branch .LBB0_311
